# rowpass B: second-pass row loads and table entries issued with the first pass at the row top; row loads as global_load so the compiler's lgkmcnt(0) no longer serialises them
# speedup vs baseline: 1.0127x; 1.0048x over previous
.LBB0_138:
	s_and_b32 s0, s16, 0x7ff
	s_cmpk_lt_i32 s16, 0x4000
	s_cselect_b64 s[8:9], -1, 0
	s_and_b64 s[10:11], s[8:9], exec
	s_cselect_b32 s12, s0, s17
	s_cmpk_gt_u32 s0, 0x77f
	s_cselect_b64 s[10:11], -1, 0
	s_and_b64 s[10:11], s[8:9], s[10:11]
	s_ashr_i32 s8, s16, 4
	s_and_b32 s8, s8, 0xffffff80
	s_add_i32 s8, s0, s8
	s_lshl_b32 s0, s12, 8
	v_lshl_add_u64 v[26:27], v[16:17], 0, s[0:1]
	v_lshl_add_u64 v[0:1], s[6:7], 0, v[22:23]
	s_mov_b32 s0, 0xc700000
	v_add_co_u32_e32 v8, vcc, s0, v0
	s_addk_i32 s8, 0xf880
	s_nop 0
	v_addc_co_u32_e32 v9, vcc, 0, v1, vcc
	global_load_dwordx4 v[4:7], v[8:9], off
	global_load_dwordx4 v[0:3], v[8:9], off offset:64
	s_waitcnt lgkmcnt(0)
	global_load_dwordx4 v[10:13], v[26:27], off
	global_load_dwordx4 v[60:63], v[26:27], off offset:16
	global_load_dwordx4 v[64:67], v[26:27], off offset:32
	global_load_dwordx4 v[68:71], v[26:27], off offset:48
	global_load_dwordx4 v[44:47], v[8:9], off offset:2048
	global_load_dwordx4 v[48:51], v[8:9], off offset:2112
	global_load_dwordx4 v[52:55], v[26:27], off
	s_ashr_i32 s9, s8, 31
	s_lshl_b64 s[8:9], s[8:9], 10
	s_mov_b64 s[14:15], -1
	s_waitcnt vmcnt(0) lgkmcnt(0)
	v_lshlrev_b32_e32 v14, 16, v4
	v_lshlrev_b32_e32 v28, 16, v0
	v_and_b32_e32 v29, 0xffff0000, v0
	v_mov_b32_e32 v30, v10
	v_mov_b32_e32 v31, v12
	v_mov_b32_e32 v12, v11
	v_and_b32_e32 v15, 0xffff0000, v4
	v_pk_mul_f32 v[10:11], v[12:13], v[28:29]
	v_pk_mul_f32 v[28:29], v[30:31], v[28:29]
	v_pk_fma_f32 v[10:11], v[30:31], v[14:15], v[10:11] neg_lo:[0,0,1] neg_hi:[0,0,1]
	v_pk_fma_f32 v[12:13], v[12:13], v[14:15], v[28:29]
	v_cvt_pk_bf16_f32 v4, v10, v11
	v_cvt_pk_bf16_f32 v0, v12, v13
	v_mov_b32_e32 v10, v60
	v_mov_b32_e32 v11, v61
	v_mov_b32_e32 v12, v62
	v_mov_b32_e32 v13, v63
	v_lshlrev_b32_e32 v28, 16, v1
	v_and_b32_e32 v29, 0xffff0000, v1
	v_lshlrev_b32_e32 v14, 16, v5
	v_and_b32_e32 v15, 0xffff0000, v5
	v_mov_b32_e32 v30, v10
	v_mov_b32_e32 v31, v12
	v_mov_b32_e32 v12, v11
	v_pk_mul_f32 v[10:11], v[12:13], v[28:29]
	v_pk_mul_f32 v[28:29], v[30:31], v[28:29]
	v_pk_fma_f32 v[10:11], v[30:31], v[14:15], v[10:11] neg_lo:[0,0,1] neg_hi:[0,0,1]
	v_pk_fma_f32 v[12:13], v[12:13], v[14:15], v[28:29]
	v_cvt_pk_bf16_f32 v5, v10, v11
	v_cvt_pk_bf16_f32 v1, v12, v13
	v_mov_b32_e32 v10, v64
	v_mov_b32_e32 v11, v65
	v_mov_b32_e32 v12, v66
	v_mov_b32_e32 v13, v67
	v_lshlrev_b32_e32 v28, 16, v2
	v_and_b32_e32 v29, 0xffff0000, v2
	v_lshlrev_b32_e32 v14, 16, v6
	v_and_b32_e32 v15, 0xffff0000, v6
	v_mov_b32_e32 v30, v10
	v_mov_b32_e32 v31, v12
	v_mov_b32_e32 v12, v11
	v_pk_mul_f32 v[10:11], v[12:13], v[28:29]
	v_pk_mul_f32 v[28:29], v[30:31], v[28:29]
	v_pk_fma_f32 v[10:11], v[30:31], v[14:15], v[10:11] neg_lo:[0,0,1] neg_hi:[0,0,1]
	v_pk_fma_f32 v[12:13], v[12:13], v[14:15], v[28:29]
	v_cvt_pk_bf16_f32 v6, v10, v11
	v_cvt_pk_bf16_f32 v2, v12, v13
	v_mov_b32_e32 v10, v68
	v_mov_b32_e32 v11, v69
	v_mov_b32_e32 v12, v70
	v_mov_b32_e32 v13, v71
	v_lshlrev_b32_e32 v28, 16, v3
	v_and_b32_e32 v29, 0xffff0000, v3
	v_lshlrev_b32_e32 v14, 16, v7
	v_and_b32_e32 v15, 0xffff0000, v7
	v_mov_b32_e32 v31, v12
	v_mov_b32_e32 v12, v11
	v_mov_b32_e32 v30, v10
	v_pk_mul_f32 v[10:11], v[12:13], v[28:29]
	v_pk_mul_f32 v[28:29], v[30:31], v[28:29]
	v_pk_fma_f32 v[10:11], v[30:31], v[14:15], v[10:11] neg_lo:[0,0,1] neg_hi:[0,0,1]
	v_pk_fma_f32 v[12:13], v[12:13], v[14:15], v[28:29]
	v_cvt_pk_bf16_f32 v7, v10, v11
	v_cvt_pk_bf16_f32 v3, v12, v13
	flat_store_dwordx4 v[8:9], v[4:7]
	flat_store_dwordx4 v[8:9], v[0:3] offset:64
	s_and_saveexec_b64 s[12:13], s[4:5]
	s_cbranch_execz .LBB0_142
	v_lshl_add_u64 v[0:1], s[6:7], 0, v[24:25]
	v_add_co_u32_e32 v28, vcc, 0xc700000, v0
	s_mov_b64 s[14:15], 0
	s_nop 0
	v_addc_co_u32_e32 v29, vcc, 0, v1, vcc
	v_mov_b64_e32 v[12:13], v[44:45]
	v_mov_b64_e32 v[14:15], v[46:47]
	v_mov_b64_e32 v[8:9], v[48:49]
	v_mov_b64_e32 v[10:11], v[50:51]
	v_mov_b64_e32 v[0:1], v[52:53]
	v_mov_b64_e32 v[2:3], v[54:55]
	v_mov_b64_e32 v[36:37], v[60:61]
	v_mov_b64_e32 v[38:39], v[62:63]
	s_and_b64 vcc, exec, s[10:11]
	v_lshlrev_b32_e32 v6, 16, v12
	v_lshlrev_b32_e32 v30, 16, v8
	v_and_b32_e32 v31, 0xffff0000, v8
	v_mov_b32_e32 v33, v2
	v_mov_b32_e32 v2, v1
	v_and_b32_e32 v7, 0xffff0000, v12
	v_mov_b32_e32 v32, v0
	v_pk_mul_f32 v[0:1], v[2:3], v[30:31]
	v_lshlrev_b32_e32 v8, 16, v9
	v_pk_fma_f32 v[4:5], v[32:33], v[6:7], v[0:1] neg_lo:[0,0,1] neg_hi:[0,0,1]
	v_pk_mul_f32 v[0:1], v[32:33], v[30:31]
	v_and_b32_e32 v9, 0xffff0000, v9
	v_pk_fma_f32 v[0:1], v[2:3], v[6:7], v[0:1]
	v_lshlrev_b32_e32 v2, 16, v13
	v_and_b32_e32 v3, 0xffff0000, v13
	v_mov_b32_e32 v12, v36
	v_mov_b32_e32 v13, v38
	v_mov_b32_e32 v38, v37
	v_pk_mul_f32 v[6:7], v[38:39], v[8:9]
	v_pk_mul_f32 v[8:9], v[12:13], v[8:9]
	v_pk_fma_f32 v[6:7], v[12:13], v[2:3], v[6:7] neg_lo:[0,0,1] neg_hi:[0,0,1]
	v_pk_fma_f32 v[2:3], v[38:39], v[2:3], v[8:9]
	v_mov_b32_e32 v36, v64
	v_mov_b32_e32 v37, v65
	v_mov_b32_e32 v38, v66
	v_mov_b32_e32 v39, v67
	v_lshlrev_b32_e32 v32, 16, v10
	v_and_b32_e32 v33, 0xffff0000, v10
	v_lshlrev_b32_e32 v8, 16, v14
	v_and_b32_e32 v9, 0xffff0000, v14
	v_lshlrev_b32_e32 v10, 16, v11
	v_and_b32_e32 v11, 0xffff0000, v11
	v_cvt_pk_bf16_f32 v30, v4, v5
	v_cvt_pk_bf16_f32 v31, v6, v7
	v_cvt_pk_bf16_f32 v34, v0, v1
	v_cvt_pk_bf16_f32 v35, v2, v3
	v_mov_b32_e32 v40, v36
	v_mov_b32_e32 v41, v38
	v_mov_b32_e32 v38, v37
	v_pk_mul_f32 v[12:13], v[38:39], v[32:33]
	v_pk_mul_f32 v[32:33], v[40:41], v[32:33]
	v_pk_fma_f32 v[12:13], v[40:41], v[8:9], v[12:13] neg_lo:[0,0,1] neg_hi:[0,0,1]
	v_pk_fma_f32 v[8:9], v[38:39], v[8:9], v[32:33]
	v_mov_b32_e32 v38, v68
	v_mov_b32_e32 v39, v69
	v_mov_b32_e32 v40, v70
	v_mov_b32_e32 v41, v71
	v_lshlrev_b32_e32 v26, 16, v15
	v_and_b32_e32 v27, 0xffff0000, v15
	v_cvt_pk_bf16_f32 v32, v12, v13
	v_cvt_pk_bf16_f32 v36, v8, v9
	v_mov_b32_e32 v43, v40
	v_mov_b32_e32 v40, v39
	v_mov_b32_e32 v42, v38
	v_pk_mul_f32 v[14:15], v[40:41], v[10:11]
	v_pk_mul_f32 v[10:11], v[42:43], v[10:11]
	v_pk_fma_f32 v[14:15], v[42:43], v[26:27], v[14:15] neg_lo:[0,0,1] neg_hi:[0,0,1]
	v_pk_fma_f32 v[10:11], v[40:41], v[26:27], v[10:11]
	v_cvt_pk_bf16_f32 v33, v14, v15
	v_cvt_pk_bf16_f32 v37, v10, v11
	flat_store_dwordx4 v[28:29], v[30:33]
	flat_store_dwordx4 v[28:29], v[34:37] offset:64
	s_cbranch_vccz .LBB0_141
	v_lshl_add_u64 v[26:27], v[20:21], 0, s[8:9]
	v_add_co_u32_e32 v26, vcc, 0xabff000, v26
	s_mov_b64 s[14:15], -1
	s_nop 0
	v_addc_co_u32_e32 v27, vcc, 0, v27, vcc
	flat_store_dwordx4 v[26:27], v[4:7]
	flat_store_dwordx4 v[26:27], v[12:15] offset:16
	flat_store_dwordx4 v[26:27], v[0:3] offset:128
	flat_store_dwordx4 v[26:27], v[8:11] offset:144
